# v24 + prologue transposes: gamma/beta loads issued with the weight loads (before the LDS barrier)
# speedup vs baseline: 1.0163x; 1.0061x over previous
; #define LAS __attribute__((address_space(3)))
; #define GASP __attribute__((address_space(1)))
; __device__ __forceinline__ void transpose_item(const float* W, int K, int N, bf16_t* WT, int item, int gu, LAS float* tile,
;                                                const float* gam = nullptr, const float* bet = nullptr, float* c1p = nullptr, float* c2p = nullptr) {
;     ...
;     { const int r = tid >> 3, c8 = (tid & 7) * 8; const float* src = W + (size_t)(k0 + r) * N + n0 + c8;
;       const f32x4 a = *(const GASP f32x4*)src, b = *(const GASP f32x4*)(src + 4);
;       LAS float* t = tile + r * 65 + c8; t[0] = a[0]; t[1] = a[1]; t[2] = a[2]; t[3] = a[3]; t[4] = b[0]; t[5] = b[1]; t[6] = b[2]; t[7] = b[3]; }
;     __syncthreads();
;     { const int n = tid >> 3, k8 = (tid & 7) * 8; const LAS float* t = tile + k8 * 65 + n;
;       float w[8];
; #pragma unroll
;       for (int i = 0; i < 8; ++i) w[i] = t[i * 65];
;       int nn = n0 + n; if (gu) nn = (nn < FF) ? ((nn >> 7) * 256 + (nn & 127)) : (((nn - FF) >> 7) * 256 + 128 + ((nn - FF) & 127));
;       float s2 = 0.f;
;       if (gam) {
; #pragma unroll
;           for (int i = 0; i < 8; ++i) { s2 += bet[k0 + k8 + i] * w[i]; w[i] *= gam[k0 + k8 + i]; }
.LBB0_39:
	s_andn2_b64 vcc, exec, s[8:9]
	s_cbranch_vccnz .LBB0_48
	s_bfe_u32 s10, s90, 0x40004
	s_lshl_b32 s11, s10, 6
	v_add_lshl_u32 v6, s11, v5, 12
	v_lshl_add_u64 v[0:1], s[42:43], 0, v[6:7]
	s_lshl_b32 s96, s91, 2
	v_lshl_add_u64 v[0:1], v[0:1], 0, s[96:97]
	v_mov_b32_e32 v9, v7
	v_lshl_add_u64 v[12:13], v[0:1], 0, v[8:9]
	global_load_dwordx4 v[0:3], v[12:13], off
	s_nop 0
	global_load_dwordx4 v[12:15], v[12:13], off offset:16
	v_readlane_b32 s60, v252, 12
	v_readlane_b32 s61, v252, 13
	v_cmp_ne_u32_e64 s[8:9], 1, v20
	s_andn2_b64 vcc, exec, s[60:61]
	s_cbranch_vccnz .Lgm_a
	v_or_b32_e32 v40, s11, v4
	v_lshlrev_b32_e32 v40, 2, v40
	global_load_dwordx4 v[24:27], v40, s[40:41]
	global_load_dwordx4 v[28:31], v40, s[40:41] offset:16
	global_load_dwordx4 v[32:35], v40, s[38:39]
	global_load_dwordx4 v[36:39], v40, s[38:39] offset:16
.Lgm_a:
	s_waitcnt vmcnt(0)
	ds_write2_b32 v18, v0, v1 offset1:1
	ds_write2_b32 v18, v2, v3 offset0:2 offset1:3
	ds_write2_b32 v18, v12, v13 offset0:4 offset1:5
	ds_write2_b32 v18, v14, v15 offset0:6 offset1:7
	s_waitcnt lgkmcnt(0)
	s_barrier
	ds_read2_b32 v[0:1], v19 offset1:65
	ds_read2_b32 v[2:3], v19 offset0:130 offset1:195
	ds_read2_b32 v[12:13], v22 offset0:4 offset1:69
	ds_read2_b32 v[14:15], v22 offset0:134 offset1:199
	s_cbranch_vccnz .LBB0_42
	s_waitcnt vmcnt(3) lgkmcnt(3)
	v_pk_mul_f32 v[16:17], v[0:1], v[24:25]
	s_nop 0
	v_add_f32_e32 v6, 0, v16
	s_waitcnt lgkmcnt(2)
	v_pk_mul_f32 v[24:25], v[2:3], v[26:27]
	v_add_f32_e32 v6, v6, v17
	v_add_f32_e32 v6, v6, v24
	s_waitcnt vmcnt(2) lgkmcnt(1)
	v_pk_mul_f32 v[26:27], v[12:13], v[28:29]
	v_add_f32_e32 v6, v6, v25
	v_add_f32_e32 v6, v6, v26
	s_waitcnt lgkmcnt(0)
	v_pk_mul_f32 v[28:29], v[14:15], v[30:31]
	v_add_f32_e32 v6, v6, v27
	v_add_f32_e32 v6, v6, v28
	s_waitcnt vmcnt(1)
	v_pk_mul_f32 v[0:1], v[0:1], v[32:33]
	v_pk_mul_f32 v[2:3], v[2:3], v[34:35]
	s_waitcnt vmcnt(0)
	v_pk_mul_f32 v[12:13], v[12:13], v[36:37]
	v_add_f32_e32 v9, v6, v29
	v_pk_mul_f32 v[14:15], v[14:15], v[38:39]
	s_branch .LBB0_43

; #define LAS __attribute__((address_space(3)))
; #define GASP __attribute__((address_space(1)))
; __device__ __forceinline__ void transpose_item(const float* W, int K, int N, bf16_t* WT, int item, int gu, LAS float* tile,
;                                                const float* gam = nullptr, const float* bet = nullptr, float* c1p = nullptr, float* c2p = nullptr) {
;     ...
;     { const int r = tid >> 3, c8 = (tid & 7) * 8; const float* src = W + (size_t)(k0 + r) * N + n0 + c8;
;       const f32x4 a = *(const GASP f32x4*)src, b = *(const GASP f32x4*)(src + 4);
;       LAS float* t = tile + r * 65 + c8; t[0] = a[0]; t[1] = a[1]; t[2] = a[2]; t[3] = a[3]; t[4] = b[0]; t[5] = b[1]; t[6] = b[2]; t[7] = b[3]; }
;     __syncthreads();
;     { const int n = tid >> 3, k8 = (tid & 7) * 8; const LAS float* t = tile + k8 * 65 + n;
;       float w[8];
; #pragma unroll
;       for (int i = 0; i < 8; ++i) w[i] = t[i * 65];
;       int nn = n0 + n; if (gu) nn = (nn < FF) ? ((nn >> 7) * 256 + (nn & 127)) : (((nn - FF) >> 7) * 256 + 128 + ((nn - FF) & 127));
;       float s2 = 0.f;
;       if (gam) {
; #pragma unroll
;           for (int i = 0; i < 8; ++i) { s2 += bet[k0 + k8 + i] * w[i]; w[i] *= gam[k0 + k8 + i]; }
.LBB0_52:
	s_andn2_b64 vcc, exec, s[8:9]
	s_cbranch_vccnz .LBB0_61
	s_add_i32 s8, s90, 0xef80
	s_and_b32 s9, s8, 0xffff
	s_mul_i32 s9, s9, 0xcccd
	s_lshr_b32 s91, s9, 21
	s_lshl_b32 s10, s91, 6
	s_mul_i32 s9, s91, 40
	v_add_u32_e32 v0, s10, v5
	s_sub_i32 s11, s8, s9
	v_mul_u32_u24_e32 v0, 0xa00, v0
	v_lshlrev_b32_e32 v6, 2, v0
	s_lshl_b32 s8, s11, 8
	v_lshl_add_u64 v[0:1], s[26:27], 0, v[6:7]
	s_and_b32 s96, s8, 0x3ff00
	v_lshl_add_u64 v[0:1], v[0:1], 0, s[96:97]
	v_mov_b32_e32 v9, v7
	v_lshl_add_u64 v[12:13], v[0:1], 0, v[8:9]
	global_load_dwordx4 v[0:3], v[12:13], off
	s_nop 0
	global_load_dwordx4 v[12:15], v[12:13], off offset:16
	v_cndmask_b32_e64 v6, 0, 1, s[92:93]
	v_cmp_ne_u32_e64 s[8:9], 1, v6
	s_andn2_b64 vcc, exec, s[92:93]
	s_cbranch_vccnz .Lgm_b
	v_or_b32_e32 v40, s10, v4
	v_lshlrev_b32_e32 v40, 2, v40
	global_load_dwordx4 v[24:27], v40, s[24:25]
	global_load_dwordx4 v[28:31], v40, s[24:25] offset:16
	global_load_dwordx4 v[32:35], v40, s[22:23]
	global_load_dwordx4 v[36:39], v40, s[22:23] offset:16

; #define LAS __attribute__((address_space(3)))
; #define GASP __attribute__((address_space(1)))
; __device__ __forceinline__ void transpose_item(const float* W, int K, int N, bf16_t* WT, int item, int gu, LAS float* tile,
;                                                const float* gam = nullptr, const float* bet = nullptr, float* c1p = nullptr, float* c2p = nullptr) {
;     ...
;     { const int r = tid >> 3, c8 = (tid & 7) * 8; const float* src = W + (size_t)(k0 + r) * N + n0 + c8;
;       const f32x4 a = *(const GASP f32x4*)src, b = *(const GASP f32x4*)(src + 4);
;       LAS float* t = tile + r * 65 + c8; t[0] = a[0]; t[1] = a[1]; t[2] = a[2]; t[3] = a[3]; t[4] = b[0]; t[5] = b[1]; t[6] = b[2]; t[7] = b[3]; }
;     __syncthreads();
;     { const int n = tid >> 3, k8 = (tid & 7) * 8; const LAS float* t = tile + k8 * 65 + n;
;       float w[8];
; #pragma unroll
;       for (int i = 0; i < 8; ++i) w[i] = t[i * 65];
;       int nn = n0 + n; if (gu) nn = (nn < FF) ? ((nn >> 7) * 256 + (nn & 127)) : (((nn - FF) >> 7) * 256 + 128 + ((nn - FF) & 127));
;       float s2 = 0.f;
;       if (gam) {
; #pragma unroll
;           for (int i = 0; i < 8; ++i) { s2 += bet[k0 + k8 + i] * w[i]; w[i] *= gam[k0 + k8 + i]; }
.LBB0_68:
	s_andn2_b64 vcc, exec, s[8:9]
	s_cbranch_vccnz .LBB0_81
	s_add_i32 s8, s90, 0xfa80
	s_and_b32 s9, s8, 0xffff
	s_mul_i32 s9, s9, 0xba2f
	s_lshr_b32 s91, s9, 22
	s_lshr_b32 s9, s9, 16
	s_mul_i32 s10, s91, 0x58
	s_sub_i32 s8, s8, s10
	s_and_b32 s10, s9, 0xffc0
	v_add_u32_e32 v0, s10, v5
	s_lshl_b32 s8, s8, 6
	v_mul_u32_u24_e32 v0, 0x1600, v0
	s_and_b32 s8, s8, 0xffc0
	v_lshlrev_b32_e32 v6, 2, v0
	v_lshl_add_u64 v[0:1], s[30:31], 0, v[6:7]
	s_lshl_b32 s96, s8, 2
	v_lshl_add_u64 v[0:1], v[0:1], 0, s[96:97]
	v_mov_b32_e32 v9, v7
	v_lshl_add_u64 v[12:13], v[0:1], 0, v[8:9]
	global_load_dwordx4 v[0:3], v[12:13], off
	s_nop 0
	global_load_dwordx4 v[12:15], v[12:13], off offset:16
	s_andn2_b64 vcc, exec, s[94:95]
	s_cbranch_vccnz .Lgm_c
	v_or_b32_e32 v40, s10, v4
	v_lshlrev_b32_e32 v40, 2, v40
	global_load_dwordx4 v[24:27], v40, s[28:29]
	global_load_dwordx4 v[28:31], v40, s[28:29] offset:16
	global_load_dwordx4 v[32:35], v40, s[50:51]
	global_load_dwordx4 v[36:39], v40, s[50:51] offset:16
.Lgm_c:
	v_add_u32_e32 v6, s8, v5
	v_cmp_lt_u32_e32 vcc, s56, v6
	v_lshlrev_b32_e32 v9, 1, v6
	v_and_b32_e32 v11, 0x7f, v6
	s_waitcnt vmcnt(0)
	ds_write2_b32 v18, v0, v1 offset1:1
	ds_write2_b32 v18, v2, v3 offset0:2 offset1:3
	ds_write2_b32 v18, v12, v13 offset0:4 offset1:5
	ds_write2_b32 v18, v14, v15 offset0:6 offset1:7
	s_waitcnt lgkmcnt(0)
	s_barrier
	ds_read2_b32 v[0:1], v19 offset1:65
	ds_read2_b32 v[2:3], v19 offset0:130 offset1:195
	ds_read2_b32 v[12:13], v22 offset0:4 offset1:69
	ds_read2_b32 v[14:15], v22 offset0:134 offset1:199
	s_and_saveexec_b64 s[8:9], vcc
	s_xor_b64 s[8:9], exec, s[8:9]
	v_add_u32_e32 v6, 0x7fffea00, v9
	v_and_b32_e32 v6, 0x7fffff00, v6
	v_or3_b32 v6, v11, v6, s57
	s_andn2_saveexec_b64 s[8:9], s[8:9]
	s_movk_i32 s11, 0x1f00
	v_and_or_b32 v6, v9, s11, v11
	s_or_b64 exec, exec, s[8:9]
	v_cndmask_b32_e64 v9, 0, 1, s[94:95]
	v_cmp_ne_u32_e64 s[8:9], 1, v9
	s_andn2_b64 vcc, exec, s[94:95]
	s_cbranch_vccnz .LBB0_75
	s_waitcnt vmcnt(3) lgkmcnt(3)
	v_pk_mul_f32 v[16:17], v[0:1], v[24:25]
	s_nop 0
	v_add_f32_e32 v9, 0, v16
	s_waitcnt lgkmcnt(2)
	v_pk_mul_f32 v[24:25], v[2:3], v[26:27]
	v_add_f32_e32 v9, v9, v17
	v_add_f32_e32 v9, v9, v24
	s_waitcnt vmcnt(2) lgkmcnt(1)
	v_pk_mul_f32 v[26:27], v[12:13], v[28:29]
	v_add_f32_e32 v9, v9, v25
	v_add_f32_e32 v9, v9, v26
	s_waitcnt lgkmcnt(0)
	v_pk_mul_f32 v[28:29], v[14:15], v[30:31]
	v_add_f32_e32 v9, v9, v27
	v_add_f32_e32 v9, v9, v28
	s_waitcnt vmcnt(1)
	v_pk_mul_f32 v[0:1], v[0:1], v[32:33]
	v_pk_mul_f32 v[2:3], v[2:3], v[34:35]
	s_waitcnt vmcnt(0)
	v_pk_mul_f32 v[12:13], v[12:13], v[36:37]
	v_add_f32_e32 v9, v9, v29
	v_pk_mul_f32 v[14:15], v[14:15], v[38:39]
	s_branch .LBB0_76
